# w_out/down GEMM epilogue: MFMA operands swapped so a lane owns an output row; 16 dwordx2 stores of cvt_pk pairs per wave instead of 64 two-byte stores
# baseline (speedup 1.0000x reference)
.Lg2_loop:
	ds_read_b128 v[148:151], v117
	ds_read_b128 v[152:155], v117 offset:4096
	ds_read_b128 v[156:159], v121 offset:32768
	ds_read_b128 v[160:163], v121 offset:40960
	s_waitcnt lgkmcnt(4)
	v_mfma_f32_32x32x16_bf16 v[50:65], v[140:143], v[132:135], v[50:65]
	s_add_u32 m0, s37, 0x4000
	s_nop 0
	global_load_lds_dwordx4 v[70:71], off
	v_lshl_add_u64 v[70:71], v[70:71], 0, s[98:99]
	v_mfma_f32_32x32x16_bf16 v[34:49], v[144:147], v[132:135], v[34:49]
	s_add_u32 m0, s37, 0xc000
	s_nop 0
	global_load_lds_dwordx4 v[78:79], off
	v_lshl_add_u64 v[78:79], v[78:79], 0, s[98:99]
	v_mfma_f32_32x32x16_bf16 v[18:33], v[140:143], v[136:139], v[18:33]
	s_add_u32 m0, s37, 0x5000
	s_nop 0
	global_load_lds_dwordx4 v[72:73], off
	v_lshl_add_u64 v[72:73], v[72:73], 0, s[98:99]
	v_mfma_f32_32x32x16_bf16 v[2:17], v[144:147], v[136:139], v[2:17]
	ds_read_b128 v[132:135], v118
	ds_read_b128 v[136:139], v118 offset:4096
	ds_read_b128 v[140:143], v122 offset:32768
	ds_read_b128 v[144:147], v122 offset:40960
	s_waitcnt lgkmcnt(4)
	v_mfma_f32_32x32x16_bf16 v[50:65], v[156:159], v[148:151], v[50:65]
	s_add_u32 m0, s37, 0xd000
	s_nop 0
	global_load_lds_dwordx4 v[80:81], off
	v_lshl_add_u64 v[80:81], v[80:81], 0, s[98:99]
	v_mfma_f32_32x32x16_bf16 v[34:49], v[160:163], v[148:151], v[34:49]
	s_add_u32 m0, s37, 0x6000
	s_nop 0
	global_load_lds_dwordx4 v[74:75], off
	v_lshl_add_u64 v[74:75], v[74:75], 0, s[98:99]
	v_mfma_f32_32x32x16_bf16 v[18:33], v[156:159], v[152:155], v[18:33]
	s_add_u32 m0, s37, 0xe000
	s_nop 0
	global_load_lds_dwordx4 v[82:83], off
	v_lshl_add_u64 v[82:83], v[82:83], 0, s[98:99]
	v_mfma_f32_32x32x16_bf16 v[2:17], v[160:163], v[152:155], v[2:17]
	ds_read_b128 v[148:151], v119
	ds_read_b128 v[152:155], v119 offset:4096
	ds_read_b128 v[156:159], v123 offset:32768
	ds_read_b128 v[160:163], v123 offset:40960
	s_waitcnt lgkmcnt(4)
	v_mfma_f32_32x32x16_bf16 v[50:65], v[140:143], v[132:135], v[50:65]
	s_add_u32 m0, s37, 0x7000
	s_nop 0
	global_load_lds_dwordx4 v[76:77], off
	v_lshl_add_u64 v[76:77], v[76:77], 0, s[98:99]
	v_mfma_f32_32x32x16_bf16 v[34:49], v[144:147], v[132:135], v[34:49]
	s_add_u32 m0, s37, 0xf000
	s_nop 0
	global_load_lds_dwordx4 v[84:85], off
	v_lshl_add_u64 v[84:85], v[84:85], 0, s[98:99]
	v_mfma_f32_32x32x16_bf16 v[18:33], v[140:143], v[136:139], v[18:33]
	v_mfma_f32_32x32x16_bf16 v[2:17], v[144:147], v[136:139], v[2:17]
	s_waitcnt vmcnt(0) lgkmcnt(0)
	s_barrier
	ds_read_b128 v[132:135], v116 offset:16384
	ds_read_b128 v[136:139], v116 offset:20480
	ds_read_b128 v[140:143], v120 offset:49152
	ds_read_b128 v[144:147], v120 offset:57344
	v_mfma_f32_32x32x16_bf16 v[50:65], v[156:159], v[148:151], v[50:65]
	v_mfma_f32_32x32x16_bf16 v[34:49], v[160:163], v[148:151], v[34:49]
	v_mfma_f32_32x32x16_bf16 v[18:33], v[156:159], v[152:155], v[18:33]
	v_mfma_f32_32x32x16_bf16 v[2:17], v[160:163], v[152:155], v[2:17]
	ds_read_b128 v[148:151], v117 offset:16384
	ds_read_b128 v[152:155], v117 offset:20480
	ds_read_b128 v[156:159], v121 offset:49152
	ds_read_b128 v[160:163], v121 offset:57344
	s_waitcnt lgkmcnt(4)
	v_mfma_f32_32x32x16_bf16 v[50:65], v[140:143], v[132:135], v[50:65]
	s_mov_b32 m0, s37
	s_nop 0
	global_load_lds_dwordx4 v[70:71], off
	v_lshl_add_u64 v[70:71], v[70:71], 0, s[98:99]
	v_mfma_f32_32x32x16_bf16 v[34:49], v[144:147], v[132:135], v[34:49]
	s_add_u32 m0, s37, 0x8000
	s_nop 0
	global_load_lds_dwordx4 v[78:79], off
	v_lshl_add_u64 v[78:79], v[78:79], 0, s[98:99]
	v_mfma_f32_32x32x16_bf16 v[18:33], v[140:143], v[136:139], v[18:33]
	s_add_u32 m0, s37, 0x1000
	s_nop 0
	global_load_lds_dwordx4 v[72:73], off
	v_lshl_add_u64 v[72:73], v[72:73], 0, s[98:99]
	v_mfma_f32_32x32x16_bf16 v[2:17], v[144:147], v[136:139], v[2:17]
	ds_read_b128 v[132:135], v118 offset:16384
	ds_read_b128 v[136:139], v118 offset:20480
	ds_read_b128 v[140:143], v122 offset:49152
	ds_read_b128 v[144:147], v122 offset:57344
	s_waitcnt lgkmcnt(4)
	v_mfma_f32_32x32x16_bf16 v[50:65], v[156:159], v[148:151], v[50:65]
	s_add_u32 m0, s37, 0x9000
	s_nop 0
	global_load_lds_dwordx4 v[80:81], off
	v_lshl_add_u64 v[80:81], v[80:81], 0, s[98:99]
	v_mfma_f32_32x32x16_bf16 v[34:49], v[160:163], v[148:151], v[34:49]
	s_add_u32 m0, s37, 0x2000
	s_nop 0
	global_load_lds_dwordx4 v[74:75], off
	v_lshl_add_u64 v[74:75], v[74:75], 0, s[98:99]
	v_mfma_f32_32x32x16_bf16 v[18:33], v[156:159], v[152:155], v[18:33]
	s_add_u32 m0, s37, 0xa000
	s_nop 0
	global_load_lds_dwordx4 v[82:83], off
	v_lshl_add_u64 v[82:83], v[82:83], 0, s[98:99]
	v_mfma_f32_32x32x16_bf16 v[2:17], v[160:163], v[152:155], v[2:17]
	ds_read_b128 v[148:151], v119 offset:16384
	ds_read_b128 v[152:155], v119 offset:20480
	ds_read_b128 v[156:159], v123 offset:49152
	ds_read_b128 v[160:163], v123 offset:57344
	s_waitcnt lgkmcnt(4)
	v_mfma_f32_32x32x16_bf16 v[50:65], v[140:143], v[132:135], v[50:65]
	s_add_u32 m0, s37, 0x3000
	s_nop 0
	global_load_lds_dwordx4 v[76:77], off
	v_lshl_add_u64 v[76:77], v[76:77], 0, s[98:99]
	v_mfma_f32_32x32x16_bf16 v[34:49], v[144:147], v[132:135], v[34:49]
	s_add_u32 m0, s37, 0xb000
	s_nop 0
	global_load_lds_dwordx4 v[84:85], off
	v_lshl_add_u64 v[84:85], v[84:85], 0, s[98:99]
	v_mfma_f32_32x32x16_bf16 v[18:33], v[140:143], v[136:139], v[18:33]
	v_mfma_f32_32x32x16_bf16 v[2:17], v[144:147], v[136:139], v[2:17]
	s_waitcnt vmcnt(0) lgkmcnt(0)
	s_barrier
	ds_read_b128 v[132:135], v116
	ds_read_b128 v[136:139], v116 offset:4096
	ds_read_b128 v[140:143], v120 offset:32768
	ds_read_b128 v[144:147], v120 offset:40960
	v_mfma_f32_32x32x16_bf16 v[50:65], v[156:159], v[148:151], v[50:65]
	v_mfma_f32_32x32x16_bf16 v[34:49], v[160:163], v[148:151], v[34:49]
	v_mfma_f32_32x32x16_bf16 v[18:33], v[156:159], v[152:155], v[18:33]
	v_mfma_f32_32x32x16_bf16 v[2:17], v[160:163], v[152:155], v[2:17]
	s_sub_u32 s39, s39, 1
	s_cmp_lg_u32 s39, 0
	s_cbranch_scc1 .Lg2_loop
	ds_read_b128 v[148:151], v117
	ds_read_b128 v[152:155], v117 offset:4096
	ds_read_b128 v[156:159], v121 offset:32768
	ds_read_b128 v[160:163], v121 offset:40960
	s_waitcnt lgkmcnt(4)
	v_mfma_f32_32x32x16_bf16 v[50:65], v[140:143], v[132:135], v[50:65]
	s_add_u32 m0, s37, 0x4000
	s_nop 0
	global_load_lds_dwordx4 v[70:71], off
	v_lshl_add_u64 v[70:71], v[70:71], 0, s[98:99]
	v_mfma_f32_32x32x16_bf16 v[34:49], v[144:147], v[132:135], v[34:49]
	s_add_u32 m0, s37, 0xc000
	s_nop 0
	global_load_lds_dwordx4 v[78:79], off
	v_lshl_add_u64 v[78:79], v[78:79], 0, s[98:99]
	v_mfma_f32_32x32x16_bf16 v[18:33], v[140:143], v[136:139], v[18:33]
	s_add_u32 m0, s37, 0x5000
	s_nop 0
	global_load_lds_dwordx4 v[72:73], off
	v_lshl_add_u64 v[72:73], v[72:73], 0, s[98:99]
	v_mfma_f32_32x32x16_bf16 v[2:17], v[144:147], v[136:139], v[2:17]
	ds_read_b128 v[132:135], v118
	ds_read_b128 v[136:139], v118 offset:4096
	ds_read_b128 v[140:143], v122 offset:32768
	ds_read_b128 v[144:147], v122 offset:40960
	s_waitcnt lgkmcnt(4)
	v_mfma_f32_32x32x16_bf16 v[50:65], v[156:159], v[148:151], v[50:65]
	s_add_u32 m0, s37, 0xd000
	s_nop 0
	global_load_lds_dwordx4 v[80:81], off
	v_lshl_add_u64 v[80:81], v[80:81], 0, s[98:99]
	v_mfma_f32_32x32x16_bf16 v[34:49], v[160:163], v[148:151], v[34:49]
	s_add_u32 m0, s37, 0x6000
	s_nop 0
	global_load_lds_dwordx4 v[74:75], off
	v_lshl_add_u64 v[74:75], v[74:75], 0, s[98:99]
	v_mfma_f32_32x32x16_bf16 v[18:33], v[156:159], v[152:155], v[18:33]
	s_add_u32 m0, s37, 0xe000
	s_nop 0
	global_load_lds_dwordx4 v[82:83], off
	v_lshl_add_u64 v[82:83], v[82:83], 0, s[98:99]
	v_mfma_f32_32x32x16_bf16 v[2:17], v[160:163], v[152:155], v[2:17]
	ds_read_b128 v[148:151], v119
	ds_read_b128 v[152:155], v119 offset:4096
	ds_read_b128 v[156:159], v123 offset:32768
	ds_read_b128 v[160:163], v123 offset:40960
	s_waitcnt lgkmcnt(4)
	v_mfma_f32_32x32x16_bf16 v[50:65], v[140:143], v[132:135], v[50:65]
	s_add_u32 m0, s37, 0x7000
	s_nop 0
	global_load_lds_dwordx4 v[76:77], off
	v_lshl_add_u64 v[76:77], v[76:77], 0, s[98:99]
	v_mfma_f32_32x32x16_bf16 v[34:49], v[144:147], v[132:135], v[34:49]
	s_add_u32 m0, s37, 0xf000
	s_nop 0
	global_load_lds_dwordx4 v[84:85], off
	v_lshl_add_u64 v[84:85], v[84:85], 0, s[98:99]
	v_mfma_f32_32x32x16_bf16 v[18:33], v[140:143], v[136:139], v[18:33]
	v_mfma_f32_32x32x16_bf16 v[2:17], v[144:147], v[136:139], v[2:17]
	s_waitcnt vmcnt(0) lgkmcnt(0)
	s_barrier
	ds_read_b128 v[132:135], v116 offset:16384
	ds_read_b128 v[136:139], v116 offset:20480
	ds_read_b128 v[140:143], v120 offset:49152
	ds_read_b128 v[144:147], v120 offset:57344
	v_mfma_f32_32x32x16_bf16 v[50:65], v[156:159], v[148:151], v[50:65]
	v_mfma_f32_32x32x16_bf16 v[34:49], v[160:163], v[148:151], v[34:49]
	v_mfma_f32_32x32x16_bf16 v[18:33], v[156:159], v[152:155], v[18:33]
	v_mfma_f32_32x32x16_bf16 v[2:17], v[160:163], v[152:155], v[2:17]
	ds_read_b128 v[148:151], v117 offset:16384
	ds_read_b128 v[152:155], v117 offset:20480
	ds_read_b128 v[156:159], v121 offset:49152
	ds_read_b128 v[160:163], v121 offset:57344
	s_waitcnt lgkmcnt(4)
	v_mfma_f32_32x32x16_bf16 v[50:65], v[140:143], v[132:135], v[50:65]
	v_mfma_f32_32x32x16_bf16 v[34:49], v[144:147], v[132:135], v[34:49]
	v_mfma_f32_32x32x16_bf16 v[18:33], v[140:143], v[136:139], v[18:33]
	v_mfma_f32_32x32x16_bf16 v[2:17], v[144:147], v[136:139], v[2:17]
	ds_read_b128 v[132:135], v118 offset:16384
	ds_read_b128 v[136:139], v118 offset:20480
	ds_read_b128 v[140:143], v122 offset:49152
	ds_read_b128 v[144:147], v122 offset:57344
	s_waitcnt lgkmcnt(4)
	v_mfma_f32_32x32x16_bf16 v[50:65], v[156:159], v[148:151], v[50:65]
	v_mfma_f32_32x32x16_bf16 v[34:49], v[160:163], v[148:151], v[34:49]
	v_mfma_f32_32x32x16_bf16 v[18:33], v[156:159], v[152:155], v[18:33]
	v_mfma_f32_32x32x16_bf16 v[2:17], v[160:163], v[152:155], v[2:17]
	ds_read_b128 v[148:151], v119 offset:16384
	ds_read_b128 v[152:155], v119 offset:20480
	ds_read_b128 v[156:159], v123 offset:49152
	ds_read_b128 v[160:163], v123 offset:57344
	s_waitcnt lgkmcnt(4)
	v_mfma_f32_32x32x16_bf16 v[50:65], v[140:143], v[132:135], v[50:65]
	v_mfma_f32_32x32x16_bf16 v[34:49], v[144:147], v[132:135], v[34:49]
	v_mfma_f32_32x32x16_bf16 v[18:33], v[140:143], v[136:139], v[18:33]
	v_mfma_f32_32x32x16_bf16 v[2:17], v[144:147], v[136:139], v[2:17]
	s_waitcnt vmcnt(0) lgkmcnt(0)
	s_barrier
	v_mfma_f32_32x32x16_bf16 v[50:65], v[156:159], v[148:151], v[50:65]
	v_mfma_f32_32x32x16_bf16 v[34:49], v[160:163], v[148:151], v[34:49]
	v_mfma_f32_32x32x16_bf16 v[18:33], v[156:159], v[152:155], v[18:33]
	v_mfma_f32_32x32x16_bf16 v[2:17], v[160:163], v[152:155], v[2:17]
	v_and_b32_e32 v70, 31, v0
	v_bfe_u32 v71, v0, 5, 1
	v_lshrrev_b32_e32 v72, 7, v0
	v_bfe_u32 v73, v0, 6, 1
	v_lshl_add_u32 v72, v72, 6, v70
	v_add_u32_e32 v72, s27, v72
	v_lshlrev_b32_e32 v73, 5, v73
	v_lshl_or_b32 v73, v71, 2, v73
	v_add_u32_e32 v73, s38, v73
	v_readlane_b32 s38, v253, 18
	v_readlane_b32 s39, v253, 19
	v_lshlrev_b32_e32 v72, 11, v72
	v_lshl_add_u32 v72, v73, 1, v72
	v_mov_b32_e32 v73, 0
	s_mov_b64 s[100:101], 0x10000
	v_lshl_add_u64 v[74:75], s[38:39], 0, v[72:73]
	v_lshl_add_u64 v[76:77], v[74:75], 0, s[100:101]
	s_nop 7
	v_cvt_pk_bf16_f32 v78, v50, v51
	v_cvt_pk_bf16_f32 v79, v52, v53
	v_cvt_pk_bf16_f32 v80, v54, v55
	v_cvt_pk_bf16_f32 v81, v56, v57
	v_cvt_pk_bf16_f32 v82, v58, v59
	v_cvt_pk_bf16_f32 v83, v60, v61
	v_cvt_pk_bf16_f32 v84, v62, v63
	v_cvt_pk_bf16_f32 v85, v64, v65
	global_store_dwordx2 v[74:75], v[78:79], off
	global_store_dwordx2 v[74:75], v[80:81], off offset:16
	global_store_dwordx2 v[74:75], v[82:83], off offset:32
	global_store_dwordx2 v[74:75], v[84:85], off offset:48
	s_nop 1
	v_cvt_pk_bf16_f32 v78, v34, v35
	v_cvt_pk_bf16_f32 v79, v36, v37
	v_cvt_pk_bf16_f32 v80, v38, v39
	v_cvt_pk_bf16_f32 v81, v40, v41
	v_cvt_pk_bf16_f32 v82, v42, v43
	v_cvt_pk_bf16_f32 v83, v44, v45
	v_cvt_pk_bf16_f32 v84, v46, v47
	v_cvt_pk_bf16_f32 v85, v48, v49
	global_store_dwordx2 v[74:75], v[78:79], off offset:128
	global_store_dwordx2 v[74:75], v[80:81], off offset:144
	global_store_dwordx2 v[74:75], v[82:83], off offset:160
	global_store_dwordx2 v[74:75], v[84:85], off offset:176
	s_nop 1
	v_cvt_pk_bf16_f32 v78, v18, v19
	v_cvt_pk_bf16_f32 v79, v20, v21
	v_cvt_pk_bf16_f32 v80, v22, v23
	v_cvt_pk_bf16_f32 v81, v24, v25
	v_cvt_pk_bf16_f32 v82, v26, v27
	v_cvt_pk_bf16_f32 v83, v28, v29
	v_cvt_pk_bf16_f32 v84, v30, v31
	v_cvt_pk_bf16_f32 v85, v32, v33
	global_store_dwordx2 v[76:77], v[78:79], off
	global_store_dwordx2 v[76:77], v[80:81], off offset:16
	global_store_dwordx2 v[76:77], v[82:83], off offset:32
	global_store_dwordx2 v[76:77], v[84:85], off offset:48
	s_nop 1
	v_cvt_pk_bf16_f32 v78, v2, v3
	v_cvt_pk_bf16_f32 v79, v4, v5
	v_cvt_pk_bf16_f32 v80, v6, v7
	v_cvt_pk_bf16_f32 v81, v8, v9
	v_cvt_pk_bf16_f32 v82, v10, v11
	v_cvt_pk_bf16_f32 v83, v12, v13
	v_cvt_pk_bf16_f32 v84, v14, v15
	v_cvt_pk_bf16_f32 v85, v16, v17
	global_store_dwordx2 v[76:77], v[78:79], off offset:128
	global_store_dwordx2 v[76:77], v[80:81], off offset:144
	global_store_dwordx2 v[76:77], v[82:83], off offset:160
	global_store_dwordx2 v[76:77], v[84:85], off offset:176
	s_nop 1
	v_readlane_b32 s38, v252, 2
	v_readlane_b32 s39, v252, 3
	s_load_dword s11, s[38:39], 0x0
	s_waitcnt lgkmcnt(0)
	s_add_i32 s16, s11, s16
	s_cmpk_gt_i32 s16, 0x1ff
	s_cbranch_scc0 .LBB0_88
